# global barrier: L1 invalidate issued at arrival behind the per-XCD arrival atomic instead of after the release
# speedup vs baseline: 1.0070x; 1.0070x over previous
; __device__ __forceinline__ unsigned xb_ld(unsigned* p)              { return __hip_atomic_load(p, __ATOMIC_RELAXED, __HIP_MEMORY_SCOPE_AGENT); }
; __device__ __forceinline__ unsigned xb_add(unsigned* p, unsigned v) { return __hip_atomic_fetch_add(p, v, __ATOMIC_RELAXED, __HIP_MEMORY_SCOPE_AGENT); }
; #define XB_SPIN(cond, bar) do { unsigned _sp = 0; while (cond) { __builtin_amdgcn_s_sleep(1); \
;     if ((++_sp & 255u) == 0u) { if (xb_ld(&(bar)[XB_TMO])) break; if (_sp > XB_SPIN_CAP) { atomicAdd(&(bar)[XB_TMO], 1u); break; } } } } while (0)
; __device__ __forceinline__ void xcd_barrier(const XcdBarrier& b) {
;     asm volatile("s_waitcnt vmcnt(0)" ::: "memory");
;     __syncthreads();
;     if (threadIdx.x == 0) {
;         unsigned* bar = b.bar;
;         __builtin_amdgcn_s_waitcnt(0);
;         unsigned nloc = b.st[0], nx = b.st[1];
;         if (nloc == 0u) { xcd_barrier_complete(bar, b.x, nloc, nx); b.st[0] = nloc; b.st[1] = nx; }
;         const unsigned old = xb_add(&bar[XB_XSUB(b.x)], 1u);
;         const unsigned gen = old / nloc;
;         if (old + 1u == (gen + 1u) * nloc) {
;             __builtin_amdgcn_fence(__ATOMIC_RELEASE, "agent");
;             asm volatile("s_waitcnt vmcnt(0)" ::: "memory");
;             const unsigned og = xb_add(&bar[XB_TOP], 1u);
;             const unsigned tg = og / nx;
;             if (og + 1u == (tg + 1u) * nx) xb_add(&bar[XB_TOPGEN], 1u);
;             else XB_SPIN(xb_ld(&bar[XB_TOPGEN]) == tg, bar);
;             __builtin_amdgcn_fence(__ATOMIC_ACQUIRE, "agent");
;             xb_add(&bar[XB_XGEN(b.x)], 1u);
;             asm volatile("s_waitcnt vmcnt(0)" ::: "memory");
;         } else {
;             XB_SPIN(xb_ld(&bar[XB_XGEN(b.x)]) == gen, bar);
.LBB0_908:
	s_mov_b64 s[8:9], exec
	v_mbcnt_lo_u32_b32 v1, s8, 0
	v_mbcnt_hi_u32_b32 v1, s9, v1
	v_cmp_eq_u32_e32 vcc, 0, v1
	s_and_saveexec_b64 s[6:7], vcc
	s_cbranch_execz .LBB0_910
	s_bcnt1_i32_b64 s8, s[8:9]
	v_mov_b32_e32 v4, s8
	v_readlane_b32 s8, v237, 32
	v_readlane_b32 s9, v237, 33
	s_nop 4
	global_atomic_add v4, v0, v4, s[8:9] sc0
	buffer_inv sc1
.LBB0_910:
	s_or_b64 exec, exec, s[6:7]
	v_cvt_f32_u32_e32 v5, v3
	s_waitcnt vmcnt(1)
	v_readfirstlane_b32 s6, v4
	v_sub_u32_e32 v4, 0, v3
	v_rcp_iflag_f32_e32 v5, v5
	v_add_u32_e32 v6, s6, v1
	v_mul_f32_e32 v5, 0x4f7ffffe, v5
	v_cvt_u32_f32_e32 v5, v5
	v_mul_lo_u32 v1, v4, v5
	v_mul_hi_u32 v1, v5, v1
	v_add_u32_e32 v1, v5, v1
	v_mul_hi_u32 v1, v6, v1
	v_mul_lo_u32 v4, v1, v3
	v_sub_u32_e32 v4, v6, v4
	v_add_u32_e32 v5, 1, v1
	v_cmp_ge_u32_e32 vcc, v4, v3
	s_nop 1
	v_cndmask_b32_e32 v1, v1, v5, vcc
	v_sub_u32_e32 v5, v4, v3
	v_cndmask_b32_e32 v4, v4, v5, vcc
	v_add_u32_e32 v5, 1, v1
	v_cmp_ge_u32_e32 vcc, v4, v3
	v_add_u32_e32 v4, 1, v6
	s_nop 0
	v_cndmask_b32_e32 v1, v1, v5, vcc
	v_mul_lo_u32 v5, v3, v1
	v_add_u32_e32 v3, v5, v3
	v_cmp_ne_u32_e32 vcc, v4, v3
	s_and_saveexec_b64 s[6:7], vcc
	s_xor_b64 s[6:7], exec, s[6:7]
	s_cbranch_execz .LBB0_924
	v_readlane_b32 s8, v237, 34
	v_readlane_b32 s9, v237, 35
	s_waitcnt lgkmcnt(0)
	s_nop 3
	global_load_dword v2, v0, s[8:9] sc1
	s_waitcnt vmcnt(0)
	v_cmp_eq_u32_e32 vcc, v2, v1
	s_and_saveexec_b64 s[8:9], vcc
	s_cbranch_execz .LBB0_923
	s_mov_b32 s20, 1
	s_mov_b64 s[10:11], 0
	s_branch .LBB0_914

; __device__ __forceinline__ unsigned xb_ld(unsigned* p)              { return __hip_atomic_load(p, __ATOMIC_RELAXED, __HIP_MEMORY_SCOPE_AGENT); }
; #define XB_SPIN(cond, bar) do { unsigned _sp = 0; while (cond) { __builtin_amdgcn_s_sleep(1); \
;     if ((++_sp & 255u) == 0u) { if (xb_ld(&(bar)[XB_TMO])) break; if (_sp > XB_SPIN_CAP) { atomicAdd(&(bar)[XB_TMO], 1u); break; } } } } while (0)
; __device__ __forceinline__ void xcd_barrier(const XcdBarrier& b) {
;     ...
;         } else {
;             XB_SPIN(xb_ld(&bar[XB_XGEN(b.x)]) == gen, bar);
;             __builtin_amdgcn_fence(__ATOMIC_ACQUIRE, "agent");
;             asm volatile("s_waitcnt vmcnt(0)" ::: "memory");
;         }
.LBB0_923:
	s_or_b64 exec, exec, s[8:9]
	s_waitcnt vmcnt(0)
	s_waitcnt vmcnt(0)

; __device__ __forceinline__ unsigned xb_ld(unsigned* p)              { return __hip_atomic_load(p, __ATOMIC_RELAXED, __HIP_MEMORY_SCOPE_AGENT); }
; __device__ __forceinline__ unsigned xb_add(unsigned* p, unsigned v) { return __hip_atomic_fetch_add(p, v, __ATOMIC_RELAXED, __HIP_MEMORY_SCOPE_AGENT); }
; #define XB_SPIN(cond, bar) do { unsigned _sp = 0; while (cond) { __builtin_amdgcn_s_sleep(1); \
;     if ((++_sp & 255u) == 0u) { if (xb_ld(&(bar)[XB_TMO])) break; if (_sp > XB_SPIN_CAP) { atomicAdd(&(bar)[XB_TMO], 1u); break; } } } } while (0)
; __device__ __forceinline__ void xcd_barrier(const XcdBarrier& b) {
;     ...
;         if (old + 1u == (gen + 1u) * nloc) {
;             __builtin_amdgcn_fence(__ATOMIC_RELEASE, "agent");
;             asm volatile("s_waitcnt vmcnt(0)" ::: "memory");
;             const unsigned og = xb_add(&bar[XB_TOP], 1u);
;             const unsigned tg = og / nx;
;             if (og + 1u == (tg + 1u) * nx) xb_add(&bar[XB_TOPGEN], 1u);
;             else XB_SPIN(xb_ld(&bar[XB_TOPGEN]) == tg, bar);
;             __builtin_amdgcn_fence(__ATOMIC_ACQUIRE, "agent");
;             xb_add(&bar[XB_XGEN(b.x)], 1u);
;             asm volatile("s_waitcnt vmcnt(0)" ::: "memory");
.LBB0_941:
	s_or_b64 exec, exec, s[6:7]
	s_mov_b64 s[6:7], exec
	v_mbcnt_lo_u32_b32 v1, s6, 0
	v_mbcnt_hi_u32_b32 v1, s7, v1
	v_cmp_eq_u32_e32 vcc, 0, v1
	s_waitcnt vmcnt(0)
	s_and_saveexec_b64 s[8:9], vcc
	s_cbranch_execnz .LBB0_942
	s_getpc_b64 s[98:99]
